# v58: P9 seam acquire invalidate issued before polling the panel counter
# speedup vs baseline: 1.0039x; 1.0039x over previous
.LBB0_1937:
	s_or_b64 exec, exec, s[10:11]
	s_cmp_gt_u32 s30, 63
	s_cbranch_scc1 .LBB0_1955
	s_memrealtime s[10:11]
	s_lshl_b32 s12, s6, 6
	s_ashr_i32 s13, s12, 31
	s_lshl_b64 s[12:13], s[12:13], 2
	s_add_u32 s6, s7, s12
	s_addc_u32 s7, s14, s13
	v_mov_b32_e32 v133, 0
	s_waitcnt lgkmcnt(0)
	v_mov_b64_e32 v[130:131], 0x1e8481
	buffer_inv sc1
	s_branch .LBB0_1941

.LBB0_1951:
	s_and_saveexec_b64 s[10:11], s[4:5]
	s_cbranch_execz .LBB0_1954
	s_waitcnt vmcnt(0)
	s_and_b64 exec, exec, s[2:3]
	v_cndmask_b32_e64 v130, 0, 1, s[6:7]
	v_mov_b32_e32 v131, 0
	ds_write_b32 v131, v130 offset:9216
